# cvhost LDS-transpose with 64 rows x 8 cols per slot: 32-B row reads, full 128-B line stores
# baseline (speedup 1.0000x reference)
; #define GAS __attribute__((address_space(1)))
; __device__ __forceinline__ unsigned cvt_pk_bf16(float lo, float hi) { unsigned r; asm volatile("v_cvt_pk_bf16_f32 %0, %1, %2" : "=v"(r) : "v"(lo), "v"(hi)); return r; }
; template <int NB>
; __device__ __forceinline__ void p0_batch(int it0, int stride, int lane, const P0Ptrs& a) {
;     ...
;     for (int q = 0; q < NB; ++q) {
;         const float gs = d[q].gs; const bool hk = d[q].ks != nullptr;
;         const f32x4 t0 = hk ? s0[q] * gs : (f32x4){gs, gs, gs, gs}, t1 = hk ? s1[q] * gs : (f32x4){gs, gs, gs, gs};
; #pragma unroll
;         for (int i = 0; i < 4; ++i) { v[q][i] *= t0[i]; v[q][4 + i] *= t1[i]; }
;         if (d[q].dst) {
; #pragma unroll
;             for (int e = 0; e < 4; ++e) { u32x4 o; o.x = cvt_pk_bf16(v[q][0][e], v[q][1][e]); o.y = cvt_pk_bf16(v[q][2][e], v[q][3][e]); o.z = cvt_pk_bf16(v[q][4][e], v[q][5][e]); o.w = cvt_pk_bf16(v[q][6][e], v[q][7][e]);
;                 *(GAS u32x4*)(d[q].dst + (size_t)e * d[q].ldt) = o; } }
;     }
.Lcv_nomul:
	v_readfirstlane_b32 s98, v0
	v_and_b32_e32 v76, 63, v0
	v_lshrrev_b32_e32 v77, 4, v76
	v_and_b32_e32 v78, 15, v76
	s_lshr_b32 s98, s98, 6
	s_lshl_b32 s99, s98, 10
	s_cmp_lt_u32 s98, 6
	s_mov_b32 s98, 0x24c00
	s_cselect_b32 s98, 0x1e800, s98
	s_add_i32 s98, s98, s99
	v_lshl_add_u32 v81, v76, 2, s98
	v_lshl_add_u32 v82, v76, 4, s98
	v_lshlrev_b32_e32 v83, 3, v78
	v_mad_u32_u24 v83, v77, s91, v83
	ds_write_b32 v81, v238
	ds_write_b32 v81, v239 offset:256
	ds_write_b32 v81, v240 offset:512
	ds_write_b32 v81, v241 offset:768
	ds_read_b128 v[100:103], v82
	ds_write_b32 v81, v242
	ds_write_b32 v81, v243 offset:256
	ds_write_b32 v81, v244 offset:512
	ds_write_b32 v81, v245 offset:768
	ds_read_b128 v[104:107], v82
	s_lshl_b32 s98, s91, 2
	s_add_u32 s98, s92, s98
	s_addc_u32 s99, s93, 0
	s_waitcnt lgkmcnt(0)
	v_cvt_pk_bf16_f32 v100, v100, v101
	v_cvt_pk_bf16_f32 v101, v102, v103
	v_cvt_pk_bf16_f32 v104, v104, v105
	v_cvt_pk_bf16_f32 v105, v106, v107
	global_store_dwordx2 v83, v[100:101], s[92:93]
	global_store_dwordx2 v83, v[104:105], s[98:99]
	s_lshl_b32 s98, s91, 3
	s_add_u32 s92, s92, s98
	s_addc_u32 s93, s93, 0

; template <int NB>
; __device__ __forceinline__ void p0_batch(int it0, int stride, int lane, const P0Ptrs& a) {
;     f32x4 v[NB][8], s0[NB], s1[NB]; P0Desc d[NB];
; #pragma unroll
;     for (int q = 0; q < NB; ++q) { const bool ok = it0 < NFAST / 4; d[q] = p0_desc(p0_super(ok ? it0 : 0, q), lane, a); if (!ok) d[q].dst = nullptr;
; #pragma unroll
;         for (int i = 0; i < 8; ++i) v[q][i] = __builtin_nontemporal_load((const f32x4*)(d[q].src + (size_t)i * d[q].nsrc));
;         const float* kp = d[q].ks ? d[q].ks : a.ffn_g;
;         s0[q] = *(const f32x4*)(kp); s1[q] = *(const f32x4*)(kp + 4); }
.Lcv_s2done:
.Lcv_loads:
	v_and_b32_e32 v76, 63, v0
	v_mul_u32_u24_e32 v79, s90, v76
	v_lshlrev_b32_e32 v80, 2, v76
	s_nop 0
	global_load_dwordx4 v[238:241], v79, s[88:89] nt
	global_load_dwordx4 v[242:245], v79, s[88:89] offset:16 nt
	global_load_dword v237, v80, s[94:95]
	s_add_u32 s88, s88, 32
	s_addc_u32 s89, s89, 0
	s_and_b32 s98, s87, 3
	s_cmp_lg_u32 s98, 3
	s_cbranch_scc1 .Lcv_inc
	s_cmp_gt_u32 s87, 18
	s_cbranch_scc1 .Lcv_inc
	s_add_i32 s99, s32, 1
	s_movk_i32 s98, 0x78
	s_cmp_lt_u32 s99, 7
	s_cselect_b32 s98, 0x60, s98
	s_cmp_eq_u32 s99, 0
	s_cselect_b32 s98, 0x50, s98
	s_cselect_b32 s99, 0, 0x58
	s_load_dwordx2 s[88:89], s[100:101], s98
	s_cmp_eq_u32 s99, 0
	s_cbranch_scc0 .Lcv_s1b_s
	s_bfe_u32 s99, s2, 0x50003
	s_cmp_lt_u32 s99, 16
	s_cselect_b32 s99, 64, 0x48
